# scan S1c: remainder-row and own-row LDS reads fused into one batch (one LDS round trip less for odd waves), on top of the S3 value-fragment change
# baseline (speedup 1.0000x reference)
; #define LAS __attribute__((address_space(3)))
; __device__ __forceinline__ void scan_pass1(const ScanP& sp, int b, int h, int seg, LAS unsigned char* lds) {
;     ...
;             for (int s4 = 0; s4 < w; ++s4) {
;                 const LAS float* lp_ = lwS + (4 * s4) * 64 + j4;
;                 const f32x4 x0 = *(const LAS f32x4*)lp_, x1 = *(const LAS f32x4*)(lp_ + 64), x2 = *(const LAS f32x4*)(lp_ + 128), x3 = *(const LAS f32x4*)(lp_ + 192);
;                 cl += (x0 + x1) + (x2 + x3);
;             }
; #pragma unroll
;             for (int q = 0; q < 4; ++q) { const int s = 4 * w + q; const f32x4 x = *(const LAS f32x4*)(lwS + s * 64 + j4); if (s <= tt) cl += x; }
.LBB0_260:
	v_add_u32_e32 v0, s0, v162
	ds_read_b128 v[104:107], v0 offset:24576
	ds_read_b128 v[110:113], v0 offset:24832
	ds_read_b128 v[114:117], v0 offset:25088
	ds_read_b128 v[150:153], v0 offset:25344
	v_add_u32_e32 v0, s92, v162
	v_add_u32_e32 v246, s81, v162
	v_add_u32_e32 v247, s20, v162
	ds_read_b128 v[242:245], v0 offset:24576
	ds_read_b128 v[230:233], v0 offset:24832
	ds_read_b128 v[234:237], v246 offset:24576
	ds_read_b128 v[238:241], v247 offset:24576
	s_waitcnt lgkmcnt(4)
	v_pk_add_f32 v[2:3], v[106:107], v[112:113]
	v_pk_add_f32 v[104:105], v[104:105], v[110:111]
	v_pk_add_f32 v[106:107], v[116:117], v[152:153]
	v_pk_add_f32 v[110:111], v[114:115], v[150:151]
	v_pk_add_f32 v[2:3], v[2:3], v[106:107]
	v_pk_add_f32 v[104:105], v[104:105], v[110:111]
	v_pk_add_f32 v[82:83], v[82:83], v[2:3]
	v_pk_add_f32 v[80:81], v[80:81], v[104:105]
	s_branch .Ls1c_own
.LBB0_261:
	v_add_u32_e32 v0, s92, v162
	v_add_u32_e32 v246, s81, v162
	v_add_u32_e32 v247, s20, v162
	ds_read_b128 v[242:245], v0 offset:24576
	ds_read_b128 v[230:233], v0 offset:24832
	ds_read_b128 v[234:237], v246 offset:24576
	ds_read_b128 v[238:241], v247 offset:24576
.Ls1c_own:
	s_mov_b64 s[0:1], exec
	s_waitcnt lgkmcnt(0)
	s_and_b64 exec, s[0:1], s[12:13]
	v_pk_add_f32 v[82:83], v[82:83], v[244:245]
	v_pk_add_f32 v[80:81], v[80:81], v[242:243]
	s_and_b64 exec, s[0:1], s[14:15]
	v_pk_add_f32 v[82:83], v[82:83], v[232:233]
	v_pk_add_f32 v[80:81], v[80:81], v[230:231]
	s_and_b64 exec, s[0:1], s[16:17]
	v_pk_add_f32 v[82:83], v[82:83], v[236:237]
	v_pk_add_f32 v[80:81], v[80:81], v[234:235]
	s_and_b64 exec, s[0:1], s[18:19]
	v_pk_add_f32 v[82:83], v[82:83], v[240:241]
	v_pk_add_f32 v[80:81], v[80:81], v[238:239]
